# v20 + Q loads issued before the attention staging barrier (no vmcnt(0) drain) + both KN weight groups loaded together
# baseline (speedup 1.0000x reference)
.LBB0_184:
	s_or_b64 exec, exec, s[2:3]
	s_waitcnt vmcnt(0)
	v_readlane_b32 s14, v253, 21
	v_ashrrev_i32_e32 v176, 7, v88
	s_lshl_b32 s15, s10, 2
	v_lshlrev_b32_e32 v174, 4, v174
	v_mov_b32_e32 v178, s14
	ds_read_b64 v[178:179], v178
	v_add3_u32 v176, v176, s15, v174
	v_ashrrev_i32_e32 v177, 31, v176
	s_waitcnt lgkmcnt(0)
	v_lshl_add_u64 v[178:179], v[176:177], 2, v[178:179]
	global_load_dword v175, v[178:179], off
	v_pk_mul_f32 v[10:11], v[2:3], v[2:3]
	v_pk_mul_f32 v[12:13], v[4:5], v[4:5]
	v_add_f32_e32 v10, v11, v10
	v_add_f32_e32 v10, v12, v10
	v_pk_mul_f32 v[14:15], v[6:7], v[6:7]
	v_add_f32_e32 v10, v13, v10
	v_add_f32_e32 v10, v14, v10
	v_pk_mul_f32 v[16:17], v[8:9], v[8:9]
	v_add_f32_e32 v10, v15, v10
	v_add_f32_e32 v10, v16, v10
	s_waitcnt vmcnt(9)
	v_pk_mul_f32 v[26:27], v[18:19], v[18:19]
	v_add_f32_e32 v10, v17, v10
	v_add_f32_e32 v10, v26, v10
	v_pk_mul_f32 v[28:29], v[20:21], v[20:21]
	v_add_f32_e32 v10, v27, v10
	v_add_f32_e32 v10, v28, v10
	s_waitcnt vmcnt(8)
	v_pk_mul_f32 v[30:31], v[22:23], v[22:23]
	v_add_f32_e32 v10, v29, v10
	v_add_f32_e32 v10, v30, v10
	v_pk_mul_f32 v[32:33], v[24:25], v[24:25]
	v_add_f32_e32 v10, v31, v10
	v_add_f32_e32 v10, v32, v10
	v_pk_mul_f32 v[54:55], v[38:39], v[38:39]
	v_add_f32_e32 v10, v33, v10
	v_add_f32_e32 v10, v54, v10
	v_pk_mul_f32 v[56:57], v[40:41], v[40:41]
	v_add_f32_e32 v10, v55, v10
	v_add_f32_e32 v10, v56, v10
	v_pk_mul_f32 v[58:59], v[42:43], v[42:43]
	v_add_f32_e32 v10, v57, v10
	v_add_f32_e32 v10, v58, v10
	v_pk_mul_f32 v[60:61], v[44:45], v[44:45]
	v_add_f32_e32 v10, v59, v10
	v_add_f32_e32 v10, v60, v10
	v_pk_mul_f32 v[62:63], v[46:47], v[46:47]
	v_add_f32_e32 v10, v61, v10
	v_add_f32_e32 v10, v62, v10
	v_pk_mul_f32 v[64:65], v[48:49], v[48:49]
	v_add_f32_e32 v10, v63, v10
	v_add_f32_e32 v10, v64, v10
	v_pk_mul_f32 v[66:67], v[50:51], v[50:51]
	v_add_f32_e32 v10, v65, v10
	v_and_b32_e32 v12, 64, v211
	v_add_f32_e32 v10, v66, v10
	v_xor_b32_e32 v11, 1, v211
	v_add_u32_e32 v76, 64, v12
	v_pk_mul_f32 v[70:71], v[52:53], v[52:53]
	v_add_f32_e32 v10, v67, v10
	v_cmp_lt_i32_e64 s[0:1], v11, v76
	v_add_f32_e32 v10, v70, v10
	v_add_f32_e32 v10, v71, v10
	v_cndmask_b32_e64 v11, v211, v11, s[0:1]
	v_lshlrev_b32_e32 v11, 2, v11
	ds_bpermute_b32 v11, v11, v10
	s_ashr_i32 s2, s97, 7
	s_cmp_eq_u32 s6, 31
	s_cselect_b64 s[6:7], -1, 0
	s_and_b64 s[8:9], s[6:7], vcc
	s_waitcnt lgkmcnt(0)
	v_add_f32_e32 v10, v10, v11
	v_fmamk_f32 v10, v10, 0x3c800000, v240
	v_cmp_gt_f32_e64 s[0:1], s72, v10
	v_mul_f32_e32 v11, 0x4b800000, v10
	s_nop 0
	v_cndmask_b32_e64 v10, v10, v11, s[0:1]
	v_rsq_f32_e32 v10, v10
	s_nop 0
	v_mul_f32_e32 v11, 0x45800000, v10
	v_cndmask_b32_e64 v54, v10, v11, s[0:1]
	v_readlane_b32 s0, v253, 20
	s_nop 1
	v_mov_b32_e32 v10, s0
	ds_read_b64 v[10:11], v10
	s_movk_i32 s0, 0x90
	v_mul_lo_u32 v35, v34, s0
	v_add3_u32 v35, 0, v35, v36
	s_waitcnt lgkmcnt(0)
	v_lshl_add_u64 v[56:57], v[0:1], 2, v[10:11]
	global_load_dwordx4 v[26:29], v[56:57], off offset:48
	global_load_dwordx4 v[30:33], v[56:57], off offset:32
	global_load_dwordx4 v[10:13], v[56:57], off offset:16
	global_load_dwordx4 v[14:17], v[56:57], off
	global_load_dwordx4 v[200:203], v[56:57], off offset:112
	global_load_dwordx4 v[204:207], v[56:57], off offset:96
	global_load_dwordx4 v[228:231], v[56:57], off offset:80
	global_load_dwordx4 v[232:235], v[56:57], off offset:64
	s_waitcnt vmcnt(0)
	v_pk_mul_f32 v[14:15], v[14:15], v[54:55] op_sel_hi:[1,0]
	s_nop 0
	v_pk_mul_f32 v[14:15], v[2:3], v[14:15]
	v_pk_mul_f32 v[2:3], v[16:17], v[54:55] op_sel_hi:[1,0]
	v_cvt_pk_bf16_f32 v36, v14, v15
	v_pk_mul_f32 v[16:17], v[4:5], v[2:3]
	v_pk_mul_f32 v[2:3], v[10:11], v[54:55] op_sel_hi:[1,0]
	v_pk_mul_f32 v[4:5], v[28:29], v[54:55] op_sel_hi:[1,0]
	v_pk_mul_f32 v[10:11], v[6:7], v[2:3]
	v_pk_mul_f32 v[2:3], v[12:13], v[54:55] op_sel_hi:[1,0]
	v_pk_mul_f32 v[4:5], v[24:25], v[4:5]
	v_pk_mul_f32 v[12:13], v[8:9], v[2:3]
	v_pk_mul_f32 v[2:3], v[30:31], v[54:55] op_sel_hi:[1,0]
	v_cvt_pk_bf16_f32 v37, v16, v17
	v_pk_mul_f32 v[6:7], v[18:19], v[2:3]
	v_pk_mul_f32 v[2:3], v[32:33], v[54:55] op_sel_hi:[1,0]
	s_nop 0
	v_pk_mul_f32 v[8:9], v[20:21], v[2:3]
	v_pk_mul_f32 v[2:3], v[26:27], v[54:55] op_sel_hi:[1,0]
	s_nop 0
	v_pk_mul_f32 v[2:3], v[22:23], v[2:3]
	v_mov_b64_e32 v[18:19], v[200:201]
	v_mov_b64_e32 v[20:21], v[202:203]
	v_mov_b64_e32 v[22:23], v[204:205]
	v_mov_b64_e32 v[24:25], v[206:207]
	v_mov_b64_e32 v[26:27], v[228:229]
	v_mov_b64_e32 v[28:29], v[230:231]
	v_mov_b64_e32 v[30:31], v[232:233]
	v_mov_b64_e32 v[32:33], v[234:235]
	v_pk_mul_f32 v[18:19], v[54:55], v[18:19] op_sel_hi:[0,1]
	v_pk_mul_f32 v[22:23], v[22:23], v[54:55] op_sel_hi:[1,0]
	v_pk_mul_f32 v[26:27], v[26:27], v[54:55] op_sel_hi:[1,0]
	v_pk_mul_f32 v[30:31], v[30:31], v[54:55] op_sel_hi:[1,0]
	v_pk_mul_f32 v[32:33], v[32:33], v[54:55] op_sel_hi:[1,0]
	v_pk_mul_f32 v[30:31], v[38:39], v[30:31]
	v_pk_mul_f32 v[28:29], v[28:29], v[54:55] op_sel_hi:[1,0]
	v_cvt_pk_bf16_f32 v38, v10, v11
	v_cvt_pk_bf16_f32 v39, v12, v13
	v_pk_mul_f32 v[32:33], v[40:41], v[32:33]
	v_pk_mul_f32 v[26:27], v[42:43], v[26:27]
	v_pk_mul_f32 v[28:29], v[44:45], v[28:29]
	v_pk_mul_f32 v[24:25], v[24:25], v[54:55] op_sel_hi:[1,0]
	v_pk_mul_f32 v[20:21], v[54:55], v[20:21] op_sel_hi:[0,1]
	ds_write_b128 v35, v[36:39]
	v_cvt_pk_bf16_f32 v36, v6, v7
	v_cvt_pk_bf16_f32 v37, v8, v9
	v_cvt_pk_bf16_f32 v38, v2, v3
	v_cvt_pk_bf16_f32 v39, v4, v5
	v_pk_mul_f32 v[22:23], v[46:47], v[22:23]
	v_pk_mul_f32 v[24:25], v[48:49], v[24:25]
	v_pk_mul_f32 v[18:19], v[50:51], v[18:19]
	v_pk_mul_f32 v[20:21], v[52:53], v[20:21]
	ds_write_b128 v35, v[36:39] offset:16
	v_cvt_pk_bf16_f32 v36, v30, v31
	v_cvt_pk_bf16_f32 v37, v32, v33
	v_cvt_pk_bf16_f32 v38, v26, v27
	v_cvt_pk_bf16_f32 v39, v28, v29
	ds_write_b128 v35, v[36:39] offset:32
	v_cvt_pk_bf16_f32 v36, v22, v23
	v_cvt_pk_bf16_f32 v37, v24, v25
	v_cvt_pk_bf16_f32 v38, v18, v19
	v_cvt_pk_bf16_f32 v39, v20, v21
	ds_write_b128 v35, v[36:39] offset:48
	s_and_saveexec_b64 s[0:1], s[8:9]
	s_cbranch_execz .LBB0_186
	s_ashr_i32 s3, s2, 31
	v_add_u32_e32 v34, 0xffffff80, v34
	v_mov_b32_e32 v35, v1
	s_lshl_b64 s[8:9], s[2:3], 9
	v_lshl_add_u64 v[34:35], v[34:35], 2, s[8:9]
	v_or_b32_e32 v34, s10, v34
	v_readlane_b32 s8, v254, 53
	v_lshlrev_b64 v[34:35], 8, v[34:35]
	v_readlane_b32 s9, v254, 54
	s_nop 1
	v_lshl_add_u64 v[34:35], s[8:9], 0, v[34:35]
	v_lshl_add_u64 v[34:35], v[0:1], 2, v[34:35]
	global_store_dwordx4 v[34:35], v[14:17], off
	global_store_dwordx4 v[34:35], v[10:13], off offset:16
	global_store_dwordx4 v[34:35], v[6:9], off offset:32
	global_store_dwordx4 v[34:35], v[2:5], off offset:48
	global_store_dwordx4 v[34:35], v[30:33], off offset:64
	global_store_dwordx4 v[34:35], v[26:29], off offset:80
	global_store_dwordx4 v[34:35], v[22:25], off offset:96
	global_store_dwordx4 v[34:35], v[18:21], off offset:112

.LBB0_192:
	s_or_b64 exec, exec, s[0:1]
	v_readlane_b32 s2, v254, 32
	s_lshl_b32 s0, s10, 2
	v_readlane_b32 s1, v254, 41
	v_readlane_b32 s3, v254, 33
	v_lshlrev_b32_e32 v96, 3, v69
	v_ashrrev_i32_e32 v97, 31, v96
	v_lshlrev_b64 v[6:7], 1, v[96:97]
	v_lshlrev_b32_e32 v50, 2, v69
	v_xor_b32_e32 v77, 32, v211
	v_or_b32_e32 v51, 0x80, v106
	v_lshl_add_u32 v4, v88, 2, 0
	v_or_b32_e32 v5, s78, v106
	s_add_i32 s0, s0, s1
	v_mov_b64_e32 v[2:3], s[2:3]
	v_add_u32_e32 v12, 0x11c00, v4
	v_or_b32_e32 v4, s88, v5
	v_or_b32_e32 v8, s89, v5
	v_or_b32_e32 v10, s90, v5
	v_or_b32_e32 v13, s91, v5
	s_lshl_b32 s2, s0, 6
	v_mad_u64_u32 v[4:5], s[6:7], v4, s95, v[2:3]
	v_mad_u64_u32 v[8:9], s[6:7], v8, s95, v[2:3]
	v_mad_u64_u32 v[10:11], s[6:7], v10, s95, v[2:3]
	v_mad_u64_u32 v[2:3], s[6:7], v13, s95, v[2:3]
	s_ashr_i32 s3, s2, 31
	v_mad_i32_i24 v5, s79, v210, v5
	v_mad_i32_i24 v9, s79, v210, v9
	v_mad_i32_i24 v11, s79, v210, v11
	s_lshl_b64 s[6:7], s[2:3], 1
	v_mad_i32_i24 v3, s79, v210, v3
	v_lshl_add_u64 v[4:5], v[4:5], 0, s[6:7]
	v_lshl_add_u64 v[8:9], v[8:9], 0, s[6:7]
	v_lshl_add_u64 v[10:11], v[10:11], 0, s[6:7]
	v_lshl_add_u64 v[2:3], v[2:3], 0, s[6:7]
	v_lshl_add_u64 v[4:5], v[4:5], 0, v[6:7]
	v_lshl_add_u64 v[8:9], v[8:9], 0, v[6:7]
	v_lshl_add_u64 v[10:11], v[10:11], 0, v[6:7]
	v_lshl_add_u64 v[2:3], v[2:3], 0, v[6:7]
	v_readlane_b32 s1, v253, 22
	global_load_dwordx4 v[34:37], v[4:5], off offset:2112
	global_load_dwordx4 v[38:41], v[8:9], off offset:2112
	global_load_dwordx4 v[42:45], v[10:11], off offset:2112
	global_load_dwordx4 v[46:49], v[2:3], off offset:2112
	global_load_dwordx4 v[30:33], v[4:5], off offset:2048
	global_load_dwordx4 v[26:29], v[8:9], off offset:2048
	global_load_dwordx4 v[22:25], v[10:11], off offset:2048
	global_load_dwordx4 v[18:21], v[2:3], off offset:2048
	ds_write_b32 v12, v175
	s_waitcnt lgkmcnt(0)
	s_barrier
	v_mov_b32_e32 v0, s1
	v_readlane_b32 s1, v253, 23
	v_xor_b32_e32 v2, 16, v211
	v_cmp_lt_i32_e32 vcc, v2, v76
	v_mov_b32_e32 v4, s1
	s_ashr_i32 s1, s0, 31
	v_cndmask_b32_e32 v6, v211, v2, vcc
	ds_read_b64 v[2:3], v0
	ds_read_b64 v[4:5], v4
	s_lshl_b64 s[0:1], s[0:1], 2
	v_lshlrev_b32_e32 v107, 2, v6
	v_cmp_lt_i32_e32 vcc, v77, v76
	s_waitcnt lgkmcnt(1)
	v_lshl_add_u64 v[2:3], v[2:3], 0, s[0:1]
	s_waitcnt lgkmcnt(0)
	v_lshl_add_u64 v[14:15], v[96:97], 2, v[4:5]
	global_load_dword v97, v[2:3], off
	s_nop 0
	global_load_dwordx4 v[2:5], v[14:15], off offset:144
	global_load_dwordx4 v[10:13], v[14:15], off offset:128
	global_load_dwordx4 v[6:9], v[14:15], off offset:16
	s_nop 0
	global_load_dwordx4 v[14:17], v[14:15], off
	v_cndmask_b32_e32 v0, v211, v77, vcc
	s_waitcnt vmcnt(9)
	v_lshlrev_b32_e32 v52, 16, v49
	v_lshlrev_b32_e32 v104, 16, v37
	v_and_b32_e32 v105, 0xffff0000, v37
	v_lshlrev_b32_e32 v86, 16, v41
	v_and_b32_e32 v87, 0xffff0000, v41
	s_waitcnt vmcnt(8)
	v_lshlrev_b32_e32 v100, 16, v33
	v_and_b32_e32 v101, 0xffff0000, v33
	s_waitcnt vmcnt(6)
	v_lshlrev_b32_e32 v64, 16, v25
	v_and_b32_e32 v65, 0xffff0000, v25
	v_lshlrev_b32_e32 v102, 16, v36
	v_and_b32_e32 v103, 0xffff0000, v36
	v_lshlrev_b32_e32 v82, 16, v40
	v_and_b32_e32 v83, 0xffff0000, v40
	v_lshlrev_b32_e32 v36, 16, v32
	v_and_b32_e32 v37, 0xffff0000, v32
	v_lshlrev_b32_e32 v70, 16, v24
	v_and_b32_e32 v71, 0xffff0000, v24
	v_lshlrev_b32_e32 v24, 16, v35
	v_and_b32_e32 v25, 0xffff0000, v35
	v_lshlrev_b32_e32 v88, 16, v39
	v_and_b32_e32 v89, 0xffff0000, v39
	v_lshlrev_b32_e32 v74, 16, v43
	v_and_b32_e32 v75, 0xffff0000, v43
	v_lshlrev_b32_e32 v32, 16, v34
	v_and_b32_e32 v33, 0xffff0000, v34
	v_lshlrev_b32_e32 v92, 16, v38
	v_and_b32_e32 v93, 0xffff0000, v38
	v_lshlrev_b32_e32 v62, 16, v42
	v_and_b32_e32 v63, 0xffff0000, v42
	v_lshlrev_b32_e32 v42, 16, v46
	v_and_b32_e32 v43, 0xffff0000, v46
	v_lshlrev_b32_e32 v60, 16, v45
	v_and_b32_e32 v61, 0xffff0000, v45
	v_and_b32_e32 v53, 0xffff0000, v49
	v_lshlrev_b32_e32 v80, 16, v29
	v_and_b32_e32 v81, 0xffff0000, v29
	s_waitcnt vmcnt(5)
	v_lshlrev_b32_e32 v54, 16, v21
	v_and_b32_e32 v55, 0xffff0000, v21
	v_lshlrev_b32_e32 v68, 16, v44
	v_and_b32_e32 v69, 0xffff0000, v44
	v_lshlrev_b32_e32 v44, 16, v48
	v_and_b32_e32 v45, 0xffff0000, v48
	v_lshlrev_b32_e32 v84, 16, v28
	v_and_b32_e32 v85, 0xffff0000, v28
	v_lshlrev_b32_e32 v48, 16, v20
	v_and_b32_e32 v49, 0xffff0000, v20
	v_lshlrev_b32_e32 v56, 16, v47
	v_and_b32_e32 v57, 0xffff0000, v47
	v_lshlrev_b32_e32 v28, 16, v31
	v_and_b32_e32 v29, 0xffff0000, v31
	v_lshlrev_b32_e32 v90, 16, v27
	v_and_b32_e32 v91, 0xffff0000, v27
	v_lshlrev_b32_e32 v58, 16, v19
	v_and_b32_e32 v59, 0xffff0000, v19
	v_lshlrev_b32_e32 v34, 16, v30
	v_and_b32_e32 v35, 0xffff0000, v30
	v_lshlrev_b32_e32 v94, 16, v26
	v_and_b32_e32 v95, 0xffff0000, v26
	v_lshlrev_b32_e32 v72, 16, v22
	v_and_b32_e32 v73, 0xffff0000, v22
	v_lshlrev_b32_e32 v46, 16, v18
	v_and_b32_e32 v47, 0xffff0000, v18
	v_pk_mul_f32 v[18:19], v[104:105], v[104:105]
	v_pk_mul_f32 v[20:21], v[86:87], v[86:87]
	v_pk_mul_f32 v[30:31], v[102:103], v[102:103]
	v_pk_mul_f32 v[38:39], v[82:83], v[82:83]
	v_pk_mul_f32 v[98:99], v[24:25], v[24:25]
	v_pk_mul_f32 v[108:109], v[88:89], v[88:89]
	v_pk_mul_f32 v[114:115], v[32:33], v[32:33]
	v_pk_mul_f32 v[116:117], v[92:93], v[92:93]
	v_pk_mul_f32 v[118:119], v[62:63], v[62:63]
	v_pk_mul_f32 v[120:121], v[42:43], v[42:43]
	v_lshlrev_b32_e32 v66, 16, v23
	v_and_b32_e32 v67, 0xffff0000, v23
	v_pk_mul_f32 v[22:23], v[60:61], v[60:61]
	v_pk_mul_f32 v[26:27], v[52:53], v[52:53]
	v_pk_mul_f32 v[40:41], v[68:69], v[68:69]
	v_pk_mul_f32 v[78:79], v[44:45], v[44:45]
	v_pk_mul_f32 v[110:111], v[74:75], v[74:75]
	v_pk_mul_f32 v[112:113], v[56:57], v[56:57]
	v_pk_fma_f32 v[18:19], v[100:101], v[100:101], v[18:19]
	v_pk_fma_f32 v[20:21], v[80:81], v[80:81], v[20:21]
	v_pk_fma_f32 v[30:31], v[36:37], v[36:37], v[30:31]
	v_pk_fma_f32 v[38:39], v[84:85], v[84:85], v[38:39]
	v_pk_fma_f32 v[98:99], v[28:29], v[28:29], v[98:99]
	v_pk_fma_f32 v[108:109], v[90:91], v[90:91], v[108:109]
	v_pk_fma_f32 v[114:115], v[34:35], v[34:35], v[114:115]
	v_pk_fma_f32 v[116:117], v[94:95], v[94:95], v[116:117]
	v_pk_fma_f32 v[118:119], v[72:73], v[72:73], v[118:119]
	v_pk_fma_f32 v[120:121], v[46:47], v[46:47], v[120:121]
	v_pk_fma_f32 v[22:23], v[64:65], v[64:65], v[22:23]
	v_pk_fma_f32 v[26:27], v[54:55], v[54:55], v[26:27]
	v_pk_fma_f32 v[40:41], v[70:71], v[70:71], v[40:41]
	v_pk_fma_f32 v[78:79], v[48:49], v[48:49], v[78:79]
	v_pk_fma_f32 v[110:111], v[66:67], v[66:67], v[110:111]
	v_pk_fma_f32 v[112:113], v[58:59], v[58:59], v[112:113]
	v_mov_b32_e32 v122, v116
	v_mov_b32_e32 v123, v114
	v_mov_b32_e32 v114, v117
	v_mov_b32_e32 v116, v108
	v_mov_b32_e32 v117, v98
	v_mov_b32_e32 v98, v109
	v_mov_b32_e32 v108, v38
	v_mov_b32_e32 v109, v30
	v_mov_b32_e32 v30, v39
	v_mov_b32_e32 v38, v20
	v_mov_b32_e32 v39, v18
	v_mov_b32_e32 v18, v21
	v_mov_b32_e32 v20, v120
	v_mov_b32_e32 v21, v118
	v_mov_b32_e32 v118, v121
	v_mov_b32_e32 v120, v112
	v_mov_b32_e32 v121, v110
	v_mov_b32_e32 v110, v113
	v_mov_b32_e32 v112, v78
	v_mov_b32_e32 v113, v40
	v_mov_b32_e32 v40, v79
	v_mov_b32_e32 v78, v26
	v_mov_b32_e32 v79, v22
	v_mov_b32_e32 v22, v27
	v_pk_add_f32 v[26:27], v[122:123], v[114:115]
	v_pk_add_f32 v[20:21], v[20:21], v[118:119]
	v_pk_add_f32 v[26:27], v[116:117], v[26:27]
	v_pk_add_f32 v[20:21], v[120:121], v[20:21]
	v_pk_add_f32 v[26:27], v[98:99], v[26:27]
	v_pk_add_f32 v[20:21], v[110:111], v[20:21]
	v_pk_add_f32 v[26:27], v[108:109], v[26:27]
	v_pk_add_f32 v[20:21], v[112:113], v[20:21]
	v_pk_add_f32 v[26:27], v[30:31], v[26:27]
	v_pk_add_f32 v[20:21], v[40:41], v[20:21]
	v_pk_add_f32 v[26:27], v[38:39], v[26:27]
	v_pk_add_f32 v[20:21], v[78:79], v[20:21]
	v_pk_add_f32 v[18:19], v[18:19], v[26:27]
	v_pk_add_f32 v[20:21], v[22:23], v[20:21]
	ds_bpermute_b32 v23, v107, v19
	ds_bpermute_b32 v22, v107, v18
	ds_bpermute_b32 v27, v107, v21
	ds_bpermute_b32 v26, v107, v20
	v_lshlrev_b32_e32 v108, 2, v0
	v_sub_u32_e32 v0, v51, v50
	s_waitcnt lgkmcnt(2)
	v_pk_add_f32 v[18:19], v[18:19], v[22:23]
	v_cmp_gt_u32_e32 vcc, s94, v0
	s_waitcnt lgkmcnt(0)
	v_pk_add_f32 v[76:77], v[20:21], v[26:27]
	ds_bpermute_b32 v21, v108, v19
	ds_bpermute_b32 v20, v108, v18
	ds_bpermute_b32 v79, v108, v77
	ds_bpermute_b32 v78, v108, v76
	v_mov_b32_e32 v109, 0xf1c9f2ca
	v_sub_u32_e32 v22, v106, v50
	v_mov_b32_e32 v110, 0xf1c9f2ca
	s_and_saveexec_b64 s[0:1], vcc
	v_sub_u32_e32 v23, v106, v50
	v_lshl_add_u32 v23, v23, 2, s96
	ds_read_b32 v110, v23 offset:512
	s_or_b64 exec, exec, s[0:1]
	v_not_b32_e32 v23, v50
	v_add_u32_e32 v26, v51, v23
	v_cmp_gt_u32_e32 vcc, s94, v26
	s_and_saveexec_b64 s[0:1], vcc
	v_add_u32_e32 v23, v106, v23
	v_lshl_add_u32 v23, v23, 2, s96
	ds_read_b32 v109, v23 offset:512
	s_or_b64 exec, exec, s[0:1]
	v_or_b32_e32 v23, 2, v50
	v_sub_u32_e32 v26, v51, v23
	v_cmp_gt_u32_e32 vcc, s94, v26
	v_mov_b32_e32 v111, 0xf1c9f2ca
	v_mov_b32_e32 v112, 0xf1c9f2ca
	s_and_saveexec_b64 s[0:1], vcc
	v_sub_u32_e32 v23, v106, v23
	v_lshl_add_u32 v23, v23, 2, s96
	ds_read_b32 v112, v23 offset:512
	s_or_b64 exec, exec, s[0:1]
	v_or_b32_e32 v23, 3, v50
	v_sub_u32_e32 v26, v51, v23
	v_cmp_gt_u32_e32 vcc, s94, v26
	s_and_saveexec_b64 s[0:1], vcc
	v_sub_u32_e32 v23, v106, v23
	v_lshl_add_u32 v23, v23, 2, s96
	ds_read_b32 v111, v23 offset:512
	s_or_b64 exec, exec, s[0:1]
	v_add_u32_e32 v23, -16, v0
	v_cmp_gt_u32_e32 vcc, s94, v23
	v_mov_b32_e32 v113, 0xf1c9f2ca
	v_mov_b32_e32 v114, 0xf1c9f2ca
	s_and_saveexec_b64 s[0:1], vcc
	v_sub_u32_e32 v23, v106, v50
	v_lshl_add_u32 v23, v23, 2, s96
	ds_read_b32 v114, v23 offset:448
	s_or_b64 exec, exec, s[0:1]
	v_subrev_u32_e32 v23, 17, v0
	v_cmp_gt_u32_e32 vcc, s94, v23
	s_and_saveexec_b64 s[0:1], vcc
	v_sub_u32_e32 v23, v106, v50
	v_lshl_add_u32 v23, v23, 2, s96
	ds_read_b32 v113, v23 offset:444
	s_or_b64 exec, exec, s[0:1]
	v_subrev_u32_e32 v23, 18, v0
	v_cmp_gt_u32_e32 vcc, s94, v23
	v_mov_b32_e32 v115, 0xf1c9f2ca
	v_mov_b32_e32 v116, 0xf1c9f2ca
	s_and_saveexec_b64 s[0:1], vcc
	v_sub_u32_e32 v23, v106, v50
	v_lshl_add_u32 v23, v23, 2, s96
	ds_read_b32 v116, v23 offset:440
	s_or_b64 exec, exec, s[0:1]
	v_subrev_u32_e32 v23, 19, v0
	v_cmp_gt_u32_e32 vcc, s94, v23
	s_and_saveexec_b64 s[0:1], vcc
	v_sub_u32_e32 v23, v106, v50
	v_lshl_add_u32 v23, v23, 2, s96
	ds_read_b32 v115, v23 offset:436
	s_or_b64 exec, exec, s[0:1]
	v_subrev_u32_e32 v23, 32, v0
	v_cmp_gt_u32_e32 vcc, s94, v23
	v_mov_b32_e32 v117, 0xf1c9f2ca
	v_mov_b32_e32 v118, 0xf1c9f2ca
	s_and_saveexec_b64 s[0:1], vcc
	v_sub_u32_e32 v23, v106, v50
	v_lshl_add_u32 v23, v23, 2, s96
	ds_read_b32 v118, v23 offset:384
	s_or_b64 exec, exec, s[0:1]
	v_subrev_u32_e32 v23, 33, v0
	v_cmp_gt_u32_e32 vcc, s94, v23
	s_and_saveexec_b64 s[0:1], vcc
	v_sub_u32_e32 v23, v106, v50
	v_lshl_add_u32 v23, v23, 2, s96
	ds_read_b32 v117, v23 offset:380
	s_or_b64 exec, exec, s[0:1]
	v_subrev_u32_e32 v23, 34, v0
	v_cmp_gt_u32_e32 vcc, s94, v23
	v_mov_b32_e32 v119, 0xf1c9f2ca
	v_mov_b32_e32 v120, 0xf1c9f2ca
	s_and_saveexec_b64 s[0:1], vcc
	v_sub_u32_e32 v23, v106, v50
	v_lshl_add_u32 v23, v23, 2, s96
	ds_read_b32 v120, v23 offset:376
	s_or_b64 exec, exec, s[0:1]
	v_subrev_u32_e32 v23, 35, v0
	v_cmp_gt_u32_e32 vcc, s94, v23
	s_and_saveexec_b64 s[0:1], vcc
	v_sub_u32_e32 v23, v106, v50
	v_lshl_add_u32 v23, v23, 2, s96
	ds_read_b32 v119, v23 offset:372
	s_or_b64 exec, exec, s[0:1]
	v_subrev_u32_e32 v23, 48, v0
	v_cmp_gt_u32_e32 vcc, s94, v23
	v_mov_b32_e32 v121, 0xf1c9f2ca
	v_mov_b32_e32 v122, 0xf1c9f2ca
	s_and_saveexec_b64 s[0:1], vcc
	v_sub_u32_e32 v23, v106, v50
	v_lshl_add_u32 v23, v23, 2, s96
	ds_read_b32 v122, v23 offset:320
	s_or_b64 exec, exec, s[0:1]
	v_subrev_u32_e32 v23, 49, v0
	v_cmp_gt_u32_e32 vcc, s94, v23
	s_and_saveexec_b64 s[0:1], vcc
	v_sub_u32_e32 v23, v106, v50
	v_lshl_add_u32 v23, v23, 2, s96
	ds_read_b32 v121, v23 offset:316
	s_or_b64 exec, exec, s[0:1]
	v_subrev_u32_e32 v23, 50, v0
	v_cmp_gt_u32_e32 vcc, s94, v23
	v_mov_b32_e32 v123, 0xf1c9f2ca
	v_mov_b32_e32 v124, 0xf1c9f2ca
	s_and_saveexec_b64 s[0:1], vcc
	v_sub_u32_e32 v23, v106, v50
	v_lshl_add_u32 v23, v23, 2, s96
	ds_read_b32 v124, v23 offset:312
	s_or_b64 exec, exec, s[0:1]
	v_subrev_u32_e32 v23, 51, v0
	v_cmp_gt_u32_e32 vcc, s94, v23
	s_and_saveexec_b64 s[0:1], vcc
	v_sub_u32_e32 v23, v106, v50
	v_lshl_add_u32 v23, v23, 2, s96
	ds_read_b32 v123, v23 offset:308
	s_or_b64 exec, exec, s[0:1]
	v_subrev_u32_e32 v23, 64, v0
	v_cmp_gt_u32_e32 vcc, s94, v23
	v_mov_b32_e32 v125, 0xf1c9f2ca
	v_mov_b32_e32 v126, 0xf1c9f2ca
	s_and_saveexec_b64 s[0:1], vcc
	v_sub_u32_e32 v23, v106, v50
	v_lshl_add_u32 v23, v23, 2, s96
	ds_read_b32 v126, v23 offset:256
	s_or_b64 exec, exec, s[0:1]
	v_add_u32_e32 v23, 0xffffffbf, v0
	v_cmp_gt_u32_e32 vcc, s94, v23
	s_and_saveexec_b64 s[0:1], vcc
	v_sub_u32_e32 v23, v106, v50
	v_lshl_add_u32 v23, v23, 2, s96
	ds_read_b32 v125, v23 offset:252
	s_or_b64 exec, exec, s[0:1]
	v_add_u32_e32 v23, 0xffffffbe, v0
	v_cmp_gt_u32_e32 vcc, s94, v23
	v_mov_b32_e32 v127, 0xf1c9f2ca
	v_mov_b32_e32 v128, 0xf1c9f2ca
	s_and_saveexec_b64 s[0:1], vcc
	v_sub_u32_e32 v23, v106, v50
	v_lshl_add_u32 v23, v23, 2, s96
	ds_read_b32 v128, v23 offset:248
	s_or_b64 exec, exec, s[0:1]
	v_add_u32_e32 v23, 0xffffffbd, v0
	v_cmp_gt_u32_e32 vcc, s94, v23
	s_and_saveexec_b64 s[0:1], vcc
	v_sub_u32_e32 v23, v106, v50
	v_lshl_add_u32 v23, v23, 2, s96
	ds_read_b32 v127, v23 offset:244
	s_or_b64 exec, exec, s[0:1]
	v_add_u32_e32 v23, 0xffffffb0, v0
	v_cmp_gt_u32_e32 vcc, s94, v23
	v_mov_b32_e32 v129, 0xf1c9f2ca
	v_mov_b32_e32 v130, 0xf1c9f2ca
	s_and_saveexec_b64 s[0:1], vcc
	v_sub_u32_e32 v23, v106, v50
	v_lshl_add_u32 v23, v23, 2, s96
	ds_read_b32 v130, v23 offset:192
	s_or_b64 exec, exec, s[0:1]
	v_add_u32_e32 v23, 0xffffffaf, v0
	v_cmp_gt_u32_e32 vcc, s94, v23
	s_and_saveexec_b64 s[0:1], vcc
	v_sub_u32_e32 v23, v106, v50
	v_lshl_add_u32 v23, v23, 2, s96
	ds_read_b32 v129, v23 offset:188
	s_or_b64 exec, exec, s[0:1]
	v_add_u32_e32 v23, 0xffffffae, v0
	v_cmp_gt_u32_e32 vcc, s94, v23
	v_mov_b32_e32 v131, 0xf1c9f2ca
	v_mov_b32_e32 v132, 0xf1c9f2ca
	s_and_saveexec_b64 s[0:1], vcc
	v_sub_u32_e32 v23, v106, v50
	v_lshl_add_u32 v23, v23, 2, s96
	ds_read_b32 v132, v23 offset:184
	s_or_b64 exec, exec, s[0:1]
	v_add_u32_e32 v23, 0xffffffad, v0
	v_cmp_gt_u32_e32 vcc, s94, v23
	s_and_saveexec_b64 s[0:1], vcc
	v_sub_u32_e32 v23, v106, v50
	v_lshl_add_u32 v23, v23, 2, s96
	ds_read_b32 v131, v23 offset:180
	s_or_b64 exec, exec, s[0:1]
	v_add_u32_e32 v23, 0xffffffa0, v0
	v_cmp_gt_u32_e32 vcc, s94, v23
	v_mov_b32_e32 v133, 0xf1c9f2ca
	v_mov_b32_e32 v134, 0xf1c9f2ca
	s_and_saveexec_b64 s[0:1], vcc
	v_sub_u32_e32 v23, v106, v50
	v_lshl_add_u32 v23, v23, 2, s96
	ds_read_b32 v134, v23 offset:128
	s_or_b64 exec, exec, s[0:1]
	v_add_u32_e32 v23, 0xffffff9f, v0
	v_cmp_gt_u32_e32 vcc, s94, v23
	s_and_saveexec_b64 s[0:1], vcc
	v_sub_u32_e32 v23, v106, v50
	v_lshl_add_u32 v23, v23, 2, s96
	ds_read_b32 v133, v23 offset:124
	s_or_b64 exec, exec, s[0:1]
	v_add_u32_e32 v23, 0xffffff9e, v0
	v_cmp_gt_u32_e32 vcc, s94, v23
	v_mov_b32_e32 v135, 0xf1c9f2ca
	v_mov_b32_e32 v136, 0xf1c9f2ca
	s_and_saveexec_b64 s[0:1], vcc
	v_sub_u32_e32 v23, v106, v50
	v_lshl_add_u32 v23, v23, 2, s96
	ds_read_b32 v136, v23 offset:120
	s_or_b64 exec, exec, s[0:1]
	v_add_u32_e32 v23, 0xffffff9d, v0
	v_cmp_gt_u32_e32 vcc, s94, v23
	s_and_saveexec_b64 s[0:1], vcc
	v_sub_u32_e32 v23, v106, v50
	v_lshl_add_u32 v23, v23, 2, s96
	ds_read_b32 v135, v23 offset:116
	s_or_b64 exec, exec, s[0:1]
	v_add_u32_e32 v23, 0xffffff90, v0
	v_cmp_gt_u32_e32 vcc, s94, v23
	v_mov_b32_e32 v137, 0xf1c9f2ca
	v_mov_b32_e32 v138, 0xf1c9f2ca
	s_and_saveexec_b64 s[0:1], vcc
	v_sub_u32_e32 v23, v106, v50
	v_lshl_add_u32 v23, v23, 2, s96
	ds_read_b32 v138, v23 offset:64
	s_or_b64 exec, exec, s[0:1]
	v_add_u32_e32 v23, 0xffffff8f, v0
	v_cmp_gt_u32_e32 vcc, s94, v23
	s_and_saveexec_b64 s[0:1], vcc
	v_sub_u32_e32 v23, v106, v50
	v_lshl_add_u32 v23, v23, 2, s96
	ds_read_b32 v137, v23 offset:60
	s_or_b64 exec, exec, s[0:1]
	v_add_u32_e32 v23, 0xffffff8e, v0
	v_cmp_gt_u32_e32 vcc, s94, v23
	v_mov_b32_e32 v139, 0xf1c9f2ca
	s_and_saveexec_b64 s[0:1], vcc
	v_sub_u32_e32 v23, v106, v50
	v_lshl_add_u32 v23, v23, 2, s96
	ds_read_b32 v139, v23 offset:56
	s_or_b64 exec, exec, s[0:1]
	v_add_u32_e32 v23, 0xffffff8d, v0
	s_movk_i32 s0, 0x7f
	v_cmp_lt_u32_e32 vcc, s0, v23
	s_and_saveexec_b64 s[0:1], vcc
	s_xor_b64 s[0:1], exec, s[0:1]
	v_sub_u32_e32 v22, v106, v50
	s_or_saveexec_b64 s[0:1], s[0:1]
	v_mov_b32_e32 v140, 0xf1c9f2ca
	v_mov_b32_e32 v141, 0xf1c9f2ca
	s_xor_b64 exec, exec, s[0:1]
	v_lshl_add_u32 v23, v22, 2, s96
	ds_read_b32 v141, v23 offset:52
	s_or_b64 exec, exec, s[0:1]
	v_cmp_gt_u32_e32 vcc, s94, v22
	s_and_saveexec_b64 s[0:1], vcc
	v_lshl_add_u32 v23, v22, 2, s96
	ds_read_b32 v140, v23
	s_or_b64 exec, exec, s[0:1]
	v_add_u32_e32 v23, 0xffffff7f, v0
	v_cmp_gt_u32_e32 vcc, s94, v23
	v_mov_b32_e32 v142, 0xf1c9f2ca
	v_lshlrev_b32_e32 v22, 2, v22
	v_mov_b32_e32 v143, 0xf1c9f2ca
	s_and_saveexec_b64 s[0:1], vcc
	v_add3_u32 v23, v22, s96, -4
	ds_read_b32 v143, v23
	s_or_b64 exec, exec, s[0:1]
	v_add_u32_e32 v23, 0xffffff7e, v0
	v_cmp_gt_u32_e32 vcc, s94, v23
	s_and_saveexec_b64 s[0:1], vcc
	v_add3_u32 v23, v22, s96, -8
	ds_read_b32 v142, v23
	s_or_b64 exec, exec, s[0:1]
	v_add_u32_e32 v0, 0xffffff7d, v0
	v_cmp_gt_u32_e32 vcc, s94, v0
	v_mov_b32_e32 v144, 0xf1c9f2ca
	s_and_saveexec_b64 s[0:1], vcc
	v_add3_u32 v0, v22, s96, -12
	ds_read_b32 v144, v0
	s_or_b64 exec, exec, s[0:1]
	s_waitcnt lgkmcnt(2)
	v_pk_add_f32 v[18:19], v[18:19], v[20:21]
	s_mov_b32 s0, 0x3c800000
	v_pk_fma_f32 v[98:99], v[18:19], s[0:1], v[240:241] op_sel_hi:[1,0,0]
	s_mov_b32 s0, 0x800000
	v_mul_f32_e32 v0, 0x4b800000, v99
	v_cmp_gt_f32_e32 vcc, s0, v99
	v_readlane_b32 s10, v254, 43
	v_readlane_b32 s18, v254, 45
	v_cndmask_b32_e32 v0, v99, v0, vcc
	v_rsq_f32_e32 v0, v0
	v_lshlrev_b32_e32 v99, 1, v96
	v_cmp_gt_f32_e64 s[62:63], s0, v98
	s_and_b64 s[0:1], s[4:5], exec
	v_mul_f32_e32 v18, 0x45800000, v0
	v_cndmask_b32_e32 v0, v0, v18, vcc
	v_mul_f32_e32 v0, 0x3e000000, v0
	s_waitcnt vmcnt(3)
	v_pk_mul_f32 v[18:19], v[4:5], v[0:1] op_sel_hi:[1,0]
	s_waitcnt vmcnt(0)
	v_pk_mul_f32 v[22:23], v[16:17], v[0:1] op_sel_hi:[1,0]
	v_pk_mul_f32 v[18:19], v[18:19], v[104:105]
	v_pk_mul_f32 v[22:23], v[22:23], v[28:29]
	v_cvt_pk_bf16_f32 v21, v18, v19
	v_pk_mul_f32 v[18:19], v[8:9], v[0:1] op_sel_hi:[1,0]
	v_cvt_pk_bf16_f32 v39, v22, v23
	v_pk_mul_f32 v[18:19], v[18:19], v[100:101]
	v_pk_mul_f32 v[22:23], v[10:11], v[0:1] op_sel_hi:[1,0]
	v_cvt_pk_bf16_f32 v41, v18, v19
	v_pk_mul_f32 v[18:19], v[2:3], v[0:1] op_sel_hi:[1,0]
	v_pk_mul_f32 v[22:23], v[22:23], v[32:33]
	v_pk_mul_f32 v[18:19], v[18:19], v[102:103]
	s_cselect_b32 s92, 0, 0x80
	v_cvt_pk_bf16_f32 v20, v18, v19
	v_pk_mul_f32 v[18:19], v[6:7], v[0:1] op_sel_hi:[1,0]
	v_readlane_b32 s46, v255, 4
	v_pk_mul_f32 v[18:19], v[18:19], v[36:37]
	s_nop 0
	v_cvt_pk_bf16_f32 v40, v18, v19
	v_pk_mul_f32 v[18:19], v[12:13], v[0:1] op_sel_hi:[1,0]
	s_nop 0
	v_pk_mul_f32 v[18:19], v[18:19], v[24:25]
	s_nop 0
	v_cvt_pk_bf16_f32 v19, v18, v19
	v_cvt_pk_bf16_f32 v18, v22, v23
	v_pk_mul_f32 v[22:23], v[14:15], v[0:1] op_sel_hi:[1,0]
	v_or_b32_e32 v0, s88, v106
	v_mul_u32_u24_e32 v0, 0x90, v0
	v_pk_mul_f32 v[22:23], v[22:23], v[34:35]
	v_add3_u32 v0, 0, v0, v99
	v_cvt_pk_bf16_f32 v38, v22, v23
	ds_read_b128 v[22:25], v0
	ds_read_b128 v[26:29], v0 offset:64
	s_waitcnt lgkmcnt(1)
	v_mfma_f32_16x16x32_bf16 v[22:25], v[22:25], v[38:41], 0
	v_or_b32_e32 v0, s89, v106
	v_mul_u32_u24_e32 v0, 0x90, v0
	v_add3_u32 v146, 0, v0, v99
	s_waitcnt lgkmcnt(0)
	v_mfma_f32_16x16x32_bf16 v[148:151], v[26:29], v[18:21], v[22:25]
	ds_read_b128 v[26:29], v146 offset:64
	v_or_b32_e32 v0, s90, v106
	v_mul_u32_u24_e32 v0, 0x90, v0
	ds_read_b128 v[22:25], v146
	s_waitcnt lgkmcnt(0)
	v_mfma_f32_16x16x32_bf16 v[22:25], v[22:25], v[38:41], 0
	v_add3_u32 v145, 0, v0, v99
	v_or_b32_e32 v0, s91, v106
	v_mul_u32_u24_e32 v0, 0x90, v0
	v_mfma_f32_16x16x32_bf16 v[152:155], v[26:29], v[18:21], v[22:25]
	ds_read_b128 v[26:29], v145 offset:64
	v_add3_u32 v105, 0, v0, v99
	v_or_b32_e32 v0, s10, v106
	s_nop 0
	ds_read_b128 v[22:25], v145
	s_waitcnt lgkmcnt(0)
	v_mfma_f32_16x16x32_bf16 v[22:25], v[22:25], v[38:41], 0
	v_mul_u32_u24_e32 v0, 0x90, v0
	v_add3_u32 v100, 0, v0, v99
	v_or_b32_e32 v0, s18, v106
	v_mfma_f32_16x16x32_bf16 v[156:159], v[26:29], v[18:21], v[22:25]
	ds_read_b128 v[26:29], v105 offset:64
	v_mul_u32_u24_e32 v0, 0x90, v0
	v_add3_u32 v101, 0, v0, v99
	s_nop 0
	ds_read_b128 v[22:25], v105
	s_waitcnt lgkmcnt(0)
	v_mfma_f32_16x16x32_bf16 v[22:25], v[22:25], v[38:41], 0
	v_or_b32_e32 v0, s73, v106
	v_mul_u32_u24_e32 v0, 0x90, v0
	v_add3_u32 v102, 0, v0, v99
	v_mfma_f32_16x16x32_bf16 v[160:163], v[26:29], v[18:21], v[22:25]
	ds_read_b128 v[26:29], v100 offset:64
	v_or_b32_e32 v0, s74, v106
	v_mul_u32_u24_e32 v0, 0x90, v0
	s_nop 0
	ds_read_b128 v[22:25], v100
	s_waitcnt lgkmcnt(0)
	v_mfma_f32_16x16x32_bf16 v[22:25], v[22:25], v[38:41], 0
	v_add3_u32 v103, 0, v0, v99
	ds_read_b128 v[170:173], v103 offset:64
	v_or_b32_e32 v0, s75, v106
	v_mfma_f32_16x16x32_bf16 v[34:37], v[26:29], v[18:21], v[22:25]
	ds_read_b128 v[26:29], v101 offset:64
	v_mul_u32_u24_e32 v0, 0x90, v0
	v_add3_u32 v104, 0, v0, v99
	s_nop 0
	ds_read_b128 v[22:25], v101
	s_waitcnt lgkmcnt(0)
	v_mfma_f32_16x16x32_bf16 v[22:25], v[22:25], v[38:41], 0
	v_add_u32_e32 v0, s88, v50
	v_cmp_le_i32_e32 vcc, s92, v0
	v_or_b32_e32 v51, 2, v0
	v_mfma_f32_16x16x32_bf16 v[30:33], v[26:29], v[18:21], v[22:25]
	ds_read_b128 v[26:29], v102 offset:64
	v_add_f32_e32 v147, v114, v152
	v_add_f32_e32 v152, v117, v157
	s_nop 0
	ds_read_b128 v[22:25], v102
	s_waitcnt lgkmcnt(0)
	v_mfma_f32_16x16x32_bf16 v[22:25], v[22:25], v[38:41], 0
	v_max_f32_e32 v147, 0xf149f2ca, v147
	v_max_f32_e32 v152, 0xf149f2ca, v152
	v_add_f32_e32 v34, v126, v34
	v_mfma_f32_16x16x32_bf16 v[26:29], v[26:29], v[18:21], v[22:25]
	v_add_f32_e32 v35, v125, v35
	v_max_f32_e32 v34, 0xf149f2ca, v34
	v_max_f32_e32 v35, 0xf149f2ca, v35
	s_nop 0
	ds_read_b128 v[22:25], v103
	s_waitcnt lgkmcnt(0)
	v_mfma_f32_16x16x32_bf16 v[22:25], v[22:25], v[38:41], 0
	v_add_f32_e32 v36, v128, v36
	v_add_f32_e32 v37, v127, v37
	v_max_f32_e32 v36, 0xf149f2ca, v36
	v_mfma_f32_16x16x32_bf16 v[22:25], v[170:173], v[18:21], v[22:25]
	ds_read_b128 v[170:173], v104
	v_max_f32_e32 v37, 0xf149f2ca, v37
	v_add_f32_e32 v30, v130, v30
	s_waitcnt lgkmcnt(0)
	v_mfma_f32_16x16x32_bf16 v[38:41], v[170:173], v[38:41], 0
	ds_read_b128 v[170:173], v104 offset:64
	v_add_f32_e32 v31, v129, v31
	v_max_f32_e32 v30, 0xf149f2ca, v30
	s_waitcnt lgkmcnt(0)
	v_mfma_f32_16x16x32_bf16 v[18:21], v[170:173], v[18:21], v[38:41]
	s_nop 2
	v_add_f32_e32 v38, v110, v148
	v_max_f32_e32 v38, 0xf149f2ca, v38
	v_cndmask_b32_e32 v39, v212, v38, vcc
	v_add_f32_e32 v38, v109, v149
	v_or_b32_e32 v40, 1, v0
	v_max_f32_e32 v38, 0xf149f2ca, v38
	v_cmp_le_i32_e32 vcc, s92, v40
	v_add_f32_e32 v41, v112, v150
	v_max_f32_e32 v41, 0xf149f2ca, v41
	v_cndmask_b32_e32 v40, v212, v38, vcc
	v_cmp_le_i32_e32 vcc, s92, v51
	v_or_b32_e32 v0, 3, v0
	v_add_f32_e32 v148, v113, v153
	v_cndmask_b32_e32 v51, v212, v41, vcc
	v_add_f32_e32 v41, v111, v151
	v_max_f32_e32 v41, 0xf149f2ca, v41
	v_cmp_le_i32_e32 vcc, s92, v0
	v_max3_f32 v38, v97, v39, v40
	v_max_f32_e32 v148, 0xf149f2ca, v148
	v_cndmask_b32_e32 v0, v212, v41, vcc
	v_add_u32_e32 v41, s89, v50
	v_or_b32_e32 v150, 2, v41
	v_cmp_gt_i32_e64 s[64:65], s92, v41
	v_or_b32_e32 v149, 1, v41
	v_cmp_gt_i32_e64 s[68:69], s92, v150
	v_add_f32_e32 v150, v115, v155
	v_or_b32_e32 v41, 3, v41
	v_cmp_gt_i32_e64 s[70:71], s92, v41
	v_max_f32_e32 v41, 0xf149f2ca, v150
	v_cmp_gt_i32_e64 s[66:67], s92, v149
	v_cndmask_b32_e64 v150, v41, v212, s[70:71]
	v_add_u32_e32 v41, s90, v50
	v_add_f32_e32 v149, v116, v154
	v_or_b32_e32 v154, 2, v41
	v_cmp_gt_i32_e64 s[54:55], s92, v41
	v_or_b32_e32 v153, 1, v41
	v_cmp_gt_i32_e64 s[58:59], s92, v154
	v_add_f32_e32 v154, v119, v159
	v_or_b32_e32 v41, 3, v41
	v_cmp_gt_i32_e64 s[60:61], s92, v41
	v_max_f32_e32 v41, 0xf149f2ca, v154
	v_cmp_gt_i32_e64 s[56:57], s92, v153
	v_cndmask_b32_e64 v154, v41, v212, s[60:61]
	v_add_u32_e32 v41, s91, v50
	v_add_f32_e32 v153, v120, v158
	v_or_b32_e32 v158, 2, v41
	v_cmp_gt_i32_e64 s[0:1], s92, v41
	v_or_b32_e32 v157, 1, v41
	v_cmp_gt_i32_e64 s[6:7], s92, v158
	v_add_f32_e32 v158, v123, v163
	v_or_b32_e32 v41, 3, v41
	v_cmp_gt_i32_e64 s[8:9], s92, v41
	v_max_f32_e32 v41, 0xf149f2ca, v158
	v_max3_f32 v38, v38, v51, v0
	v_cndmask_b32_e64 v158, v41, v212, s[8:9]
	v_add_u32_e32 v41, s10, v50
	v_or_b32_e32 v159, 1, v41
	v_cmp_gt_i32_e64 s[10:11], s92, v41
	v_cmp_gt_i32_e64 s[12:13], s92, v159
	v_or_b32_e32 v159, 2, v41
	v_or_b32_e32 v41, 3, v41
	v_cmp_gt_i32_e64 s[16:17], s92, v41
	v_add_u32_e32 v41, s18, v50
	v_cndmask_b32_e64 v147, v147, v212, s[64:65]
	v_cndmask_b32_e64 v148, v148, v212, s[66:67]
	v_max_f32_e32 v149, 0xf149f2ca, v149
	v_add_f32_e32 v151, v118, v156
	v_cmp_gt_i32_e64 s[14:15], s92, v159
	v_or_b32_e32 v159, 1, v41
	v_max3_f32 v38, v38, v147, v148
	v_cndmask_b32_e64 v149, v149, v212, s[68:69]
	v_max_f32_e32 v151, 0xf149f2ca, v151
	v_cmp_gt_i32_e64 s[18:19], s92, v41
	v_cmp_gt_i32_e64 s[20:21], s92, v159
	v_or_b32_e32 v159, 2, v41
	v_or_b32_e32 v41, 3, v41
	v_max3_f32 v38, v38, v149, v150
	v_cndmask_b32_e64 v151, v151, v212, s[54:55]
	v_cndmask_b32_e64 v152, v152, v212, s[56:57]
	v_max_f32_e32 v153, 0xf149f2ca, v153
	v_add_f32_e32 v155, v122, v160
	v_add_f32_e32 v156, v121, v161
	v_cmp_gt_i32_e64 s[24:25], s92, v41
	v_add_u32_e32 v41, s73, v50
	v_max3_f32 v38, v38, v151, v152
	v_cndmask_b32_e64 v153, v153, v212, s[58:59]
	v_max_f32_e32 v155, 0xf149f2ca, v155
	v_cmp_gt_i32_e64 s[4:5], s92, v157
	v_max_f32_e32 v156, 0xf149f2ca, v156
	v_add_f32_e32 v157, v124, v162
	v_cmp_gt_i32_e64 s[22:23], s92, v159
	v_or_b32_e32 v159, 1, v41
	v_max3_f32 v38, v38, v153, v154
	v_cndmask_b32_e64 v155, v155, v212, s[0:1]
	v_cndmask_b32_e64 v156, v156, v212, s[4:5]
	v_max_f32_e32 v157, 0xf149f2ca, v157
	v_cmp_gt_i32_e64 s[26:27], s92, v41
	v_cmp_gt_i32_e64 s[28:29], s92, v159
	v_or_b32_e32 v159, 2, v41
	v_or_b32_e32 v41, 3, v41
	v_max3_f32 v38, v38, v155, v156
	v_cndmask_b32_e64 v157, v157, v212, s[6:7]
	v_cmp_gt_i32_e64 s[34:35], s92, v41
	v_add_u32_e32 v41, s74, v50
	v_max3_f32 v38, v38, v157, v158
	v_cndmask_b32_e64 v34, v34, v212, s[10:11]
	v_cndmask_b32_e64 v35, v35, v212, s[12:13]
	v_cmp_gt_i32_e64 s[30:31], s92, v159
	v_or_b32_e32 v159, 1, v41
	v_max3_f32 v38, v38, v34, v35
	v_cndmask_b32_e64 v36, v36, v212, s[14:15]
	v_cndmask_b32_e64 v37, v37, v212, s[16:17]
	v_max_f32_e32 v31, 0xf149f2ca, v31
	v_add_f32_e32 v32, v132, v32
	v_add_f32_e32 v33, v131, v33
	v_cmp_gt_i32_e64 s[36:37], s92, v41
	v_cmp_gt_i32_e64 s[38:39], s92, v159
	v_or_b32_e32 v159, 2, v41
	v_or_b32_e32 v41, 3, v41
	v_max3_f32 v38, v38, v36, v37
	v_cndmask_b32_e64 v30, v30, v212, s[18:19]
	v_cndmask_b32_e64 v31, v31, v212, s[20:21]
	v_max_f32_e32 v32, 0xf149f2ca, v32
	v_max_f32_e32 v33, 0xf149f2ca, v33
	v_add_f32_e32 v26, v134, v26
	v_add_f32_e32 v27, v133, v27
	v_cmp_gt_i32_e64 s[42:43], s92, v41
	v_add_u32_e32 v41, s75, v50
	v_add_f32_e32 v18, v140, v18
	v_max3_f32 v38, v38, v30, v31
	v_cndmask_b32_e64 v32, v32, v212, s[22:23]
	v_cndmask_b32_e64 v33, v33, v212, s[24:25]
	v_max_f32_e32 v26, 0xf149f2ca, v26
	v_max_f32_e32 v27, 0xf149f2ca, v27
	v_add_f32_e32 v28, v136, v28
	v_add_f32_e32 v29, v135, v29
	v_cmp_gt_i32_e64 s[44:45], s92, v41
	v_max_f32_e32 v18, 0xf149f2ca, v18
	v_max3_f32 v38, v38, v32, v33
	v_cndmask_b32_e64 v26, v26, v212, s[26:27]
	v_cndmask_b32_e64 v27, v27, v212, s[28:29]
	v_max_f32_e32 v28, 0xf149f2ca, v28
	v_max_f32_e32 v29, 0xf149f2ca, v29
	v_add_f32_e32 v22, v138, v22
	v_add_f32_e32 v23, v137, v23
	v_cmp_gt_i32_e64 s[40:41], s92, v159
	v_cndmask_b32_e64 v159, v18, v212, s[44:45]
	v_add_f32_e32 v18, v143, v19
	v_or_b32_e32 v19, 1, v41
	v_max3_f32 v38, v38, v26, v27
	v_cndmask_b32_e64 v28, v28, v212, s[30:31]
	v_cndmask_b32_e64 v29, v29, v212, s[34:35]
	v_max_f32_e32 v22, 0xf149f2ca, v22
	v_max_f32_e32 v23, 0xf149f2ca, v23
	v_add_f32_e32 v24, v139, v24
	v_add_f32_e32 v25, v141, v25
	v_cmp_gt_i32_e64 s[48:49], s92, v19
	v_add_f32_e32 v19, v142, v20
	v_or_b32_e32 v20, 2, v41
	v_max3_f32 v38, v38, v28, v29
	v_cndmask_b32_e64 v22, v22, v212, s[36:37]
	v_cndmask_b32_e64 v23, v23, v212, s[38:39]
	v_max_f32_e32 v24, 0xf149f2ca, v24
	v_max_f32_e32 v25, 0xf149f2ca, v25
	v_cmp_gt_i32_e64 s[50:51], s92, v20
	v_max_f32_e32 v19, 0xf149f2ca, v19
	v_max3_f32 v38, v38, v22, v23
	v_cndmask_b32_e64 v24, v24, v212, s[40:41]
	v_cndmask_b32_e64 v25, v25, v212, s[42:43]
	v_max_f32_e32 v18, 0xf149f2ca, v18
	v_cndmask_b32_e64 v161, v19, v212, s[50:51]
	v_add_f32_e32 v19, v144, v21
	v_or_b32_e32 v20, 3, v41
	v_max3_f32 v38, v38, v24, v25
	v_cndmask_b32_e64 v160, v18, v212, s[48:49]
	v_cmp_gt_i32_e64 s[52:53], s92, v20
	v_max_f32_e32 v19, 0xf149f2ca, v19
	v_max3_f32 v18, v38, v159, v160
	v_cndmask_b32_e64 v162, v19, v212, s[52:53]
	v_max3_f32 v18, v18, v161, v162
	ds_bpermute_b32 v19, v107, v18
	s_andn2_b64 vcc, exec, s[76:77]
	s_waitcnt lgkmcnt(0)
	v_max_f32_e32 v19, v19, v19
	v_max_f32_e32 v18, v18, v19
	ds_bpermute_b32 v19, v108, v18
	s_waitcnt lgkmcnt(0)
	v_max_f32_e32 v19, v19, v19
	v_max_f32_e32 v41, v18, v19
	v_mul_u32_u24_e32 v18, 0x150, v106
	v_add3_u32 v38, s46, v18, v96
	v_sub_f32_e32 v18, v39, v41
	v_mul_f32_e32 v18, 0x3fb8aa3b, v18
	v_sub_f32_e32 v20, v40, v41
	v_exp_f32_e32 v18, v18
	v_mul_f32_e32 v20, 0x3fb8aa3b, v20
	v_sub_f32_e32 v21, v51, v41
	v_exp_f32_e32 v20, v20
	v_mul_f32_e32 v21, 0x3fb8aa3b, v21
	v_sub_f32_e32 v0, v0, v41
	v_exp_f32_e32 v21, v21
	v_mul_f32_e32 v0, 0x3fb8aa3b, v0
	v_exp_f32_e32 v0, v0
	v_add_f32_e32 v19, 0, v18
	v_add_f32_e32 v19, v20, v19
	v_add_f32_e32 v19, v21, v19
	v_add_f32_e32 v39, v0, v19
	v_cvt_pk_bf16_f32 v19, v21, v0
	v_sub_f32_e32 v0, v147, v41
	v_mul_f32_e32 v0, 0x3fb8aa3b, v0
	v_exp_f32_e32 v0, v0
	v_sub_f32_e32 v21, v148, v41
	v_cvt_pk_bf16_f32 v18, v18, v20
	v_mul_f32_e32 v21, 0x3fb8aa3b, v21
	v_add_f32_e32 v20, v0, v39
	v_sub_f32_e32 v39, v149, v41
	v_exp_f32_e32 v21, v21
	v_mul_f32_e32 v39, 0x3fb8aa3b, v39
	v_sub_f32_e32 v40, v150, v41
	v_exp_f32_e32 v39, v39
	v_mul_f32_e32 v40, 0x3fb8aa3b, v40
	v_exp_f32_e32 v40, v40
	v_add_f32_e32 v20, v21, v20
	v_add_f32_e32 v20, v39, v20
	v_readlane_b32 s46, v254, 47
	v_add_f32_e32 v51, v40, v20
	v_cvt_pk_bf16_f32 v20, v0, v21
	v_cvt_pk_bf16_f32 v21, v39, v40
	v_sub_f32_e32 v0, v151, v41
	ds_write2_b64 v38, v[18:19], v[20:21] offset1:4
	v_mul_f32_e32 v0, 0x3fb8aa3b, v0
	v_sub_f32_e32 v19, v152, v41
	v_exp_f32_e32 v0, v0
	v_mul_f32_e32 v19, 0x3fb8aa3b, v19
	v_sub_f32_e32 v20, v153, v41
	v_exp_f32_e32 v19, v19
	v_mul_f32_e32 v20, 0x3fb8aa3b, v20
	v_sub_f32_e32 v21, v154, v41
	v_exp_f32_e32 v20, v20
	v_mul_f32_e32 v21, 0x3fb8aa3b, v21
	v_exp_f32_e32 v21, v21
	v_add_f32_e32 v18, v0, v51
	v_add_f32_e32 v18, v19, v18
	v_add_f32_e32 v18, v20, v18
	v_add_f32_e32 v39, v21, v18
	v_cvt_pk_bf16_f32 v18, v0, v19
	v_sub_f32_e32 v0, v155, v41
	v_mul_f32_e32 v0, 0x3fb8aa3b, v0
	v_exp_f32_e32 v0, v0
	v_cvt_pk_bf16_f32 v19, v20, v21
	v_sub_f32_e32 v21, v156, v41
	v_mul_f32_e32 v21, 0x3fb8aa3b, v21
	v_add_f32_e32 v20, v0, v39
	v_sub_f32_e32 v39, v157, v41
	v_exp_f32_e32 v21, v21
	v_mul_f32_e32 v39, 0x3fb8aa3b, v39
	v_sub_f32_e32 v40, v158, v41
	v_exp_f32_e32 v39, v39
	v_mul_f32_e32 v40, 0x3fb8aa3b, v40
	v_exp_f32_e32 v40, v40
	v_add_f32_e32 v20, v21, v20
	v_add_f32_e32 v20, v39, v20
	v_add_f32_e32 v51, v40, v20
	v_cvt_pk_bf16_f32 v20, v0, v21
	v_cvt_pk_bf16_f32 v21, v39, v40
	v_sub_f32_e32 v0, v34, v41
	ds_write2_b64 v38, v[18:19], v[20:21] offset0:8 offset1:12
	v_mul_f32_e32 v0, 0x3fb8aa3b, v0
	v_sub_f32_e32 v19, v35, v41
	v_exp_f32_e32 v0, v0
	v_mul_f32_e32 v19, 0x3fb8aa3b, v19
	v_sub_f32_e32 v20, v36, v41
	v_exp_f32_e32 v19, v19
	v_mul_f32_e32 v20, 0x3fb8aa3b, v20
	v_sub_f32_e32 v21, v37, v41
	v_exp_f32_e32 v20, v20
	v_mul_f32_e32 v21, 0x3fb8aa3b, v21
	v_exp_f32_e32 v21, v21
	v_add_f32_e32 v18, v0, v51
	v_add_f32_e32 v18, v19, v18
	v_add_f32_e32 v18, v20, v18
	v_add_f32_e32 v34, v21, v18
	v_cvt_pk_bf16_f32 v18, v0, v19
	v_sub_f32_e32 v0, v30, v41
	v_cvt_pk_bf16_f32 v19, v20, v21
	v_mul_f32_e32 v0, 0x3fb8aa3b, v0
	v_sub_f32_e32 v21, v31, v41
	v_exp_f32_e32 v0, v0
	v_mul_f32_e32 v21, 0x3fb8aa3b, v21
	v_sub_f32_e32 v30, v32, v41
	v_exp_f32_e32 v21, v21
	v_mul_f32_e32 v30, 0x3fb8aa3b, v30
	v_sub_f32_e32 v31, v33, v41
	v_exp_f32_e32 v30, v30
	v_mul_f32_e32 v31, 0x3fb8aa3b, v31
	v_exp_f32_e32 v31, v31
	v_add_f32_e32 v20, v0, v34
	v_add_f32_e32 v20, v21, v20
	v_add_f32_e32 v20, v30, v20
	v_add_f32_e32 v32, v31, v20
	v_cvt_pk_bf16_f32 v20, v0, v21
	v_cvt_pk_bf16_f32 v21, v30, v31
	v_sub_f32_e32 v0, v26, v41
	ds_write2_b64 v38, v[18:19], v[20:21] offset0:16 offset1:20
	v_mul_f32_e32 v0, 0x3fb8aa3b, v0
	v_sub_f32_e32 v19, v27, v41
	v_exp_f32_e32 v0, v0
	v_mul_f32_e32 v19, 0x3fb8aa3b, v19
	v_sub_f32_e32 v20, v28, v41
	v_exp_f32_e32 v19, v19
	v_mul_f32_e32 v20, 0x3fb8aa3b, v20
	v_sub_f32_e32 v21, v29, v41
	v_exp_f32_e32 v20, v20
	v_mul_f32_e32 v21, 0x3fb8aa3b, v21
	v_exp_f32_e32 v21, v21
	v_add_f32_e32 v18, v0, v32
	v_add_f32_e32 v18, v19, v18
	v_add_f32_e32 v18, v20, v18
	v_add_f32_e32 v26, v21, v18
	v_cvt_pk_bf16_f32 v18, v0, v19
	v_sub_f32_e32 v0, v22, v41
	v_cvt_pk_bf16_f32 v19, v20, v21
	v_mul_f32_e32 v0, 0x3fb8aa3b, v0
	v_sub_f32_e32 v21, v23, v41
	v_exp_f32_e32 v0, v0
	v_mul_f32_e32 v21, 0x3fb8aa3b, v21
	v_sub_f32_e32 v22, v24, v41
	v_exp_f32_e32 v21, v21
	v_mul_f32_e32 v22, 0x3fb8aa3b, v22
	v_sub_f32_e32 v23, v25, v41
	v_exp_f32_e32 v22, v22
	v_mul_f32_e32 v23, 0x3fb8aa3b, v23
	v_exp_f32_e32 v23, v23
	v_add_f32_e32 v20, v0, v26
	v_add_f32_e32 v20, v21, v20
	v_add_f32_e32 v20, v22, v20
	v_add_f32_e32 v24, v23, v20
	v_cvt_pk_bf16_f32 v20, v0, v21
	v_cvt_pk_bf16_f32 v21, v22, v23
	v_sub_f32_e32 v0, v159, v41
	ds_write2_b64 v38, v[18:19], v[20:21] offset0:24 offset1:28
	v_mul_f32_e32 v0, 0x3fb8aa3b, v0
	v_sub_f32_e32 v19, v160, v41
	v_exp_f32_e32 v0, v0
	v_mul_f32_e32 v19, 0x3fb8aa3b, v19
	v_sub_f32_e32 v20, v161, v41
	v_exp_f32_e32 v19, v19
	v_mul_f32_e32 v20, 0x3fb8aa3b, v20
	v_sub_f32_e32 v21, v162, v41
	v_exp_f32_e32 v20, v20
	v_mul_f32_e32 v21, 0x3fb8aa3b, v21
	v_exp_f32_e32 v21, v21
	v_add_f32_e32 v18, v0, v24
	v_add_f32_e32 v18, v19, v18
	v_add_f32_e32 v18, v20, v18
	v_add_f32_e32 v22, v21, v18
	v_cvt_pk_bf16_f32 v18, v0, v19
	v_cvt_pk_bf16_f32 v19, v20, v21
	v_mov_b32_e32 v0, v1
	ds_write2_b64 v38, v[18:19], v[0:1] offset0:32 offset1:36
	ds_bpermute_b32 v18, v107, v22
	v_mul_u32_u24_e32 v40, 0x230, v106
	v_add_u32_e32 v39, v38, v96
	v_add3_u32 v51, s46, v99, v40
	ds_read_b128 v[26:29], v51 offset:45824
	ds_read_b128 v[30:33], v51 offset:54784
	s_waitcnt lgkmcnt(2)
	v_add_f32_e32 v147, v22, v18
	ds_read_b128 v[18:21], v39
	ds_read_b128 v[22:25], v51 offset:36864
	ds_read_b128 v[34:37], v51 offset:63744
	s_waitcnt lgkmcnt(1)
	v_mfma_f32_16x16x32_bf16 v[22:25], v[22:25], v[18:21], 0
	ds_bpermute_b32 v148, v108, v147
	v_mfma_f32_16x16x32_bf16 v[26:29], v[26:29], v[18:21], 0
	v_mfma_f32_16x16x32_bf16 v[30:33], v[30:33], v[18:21], 0
	s_waitcnt lgkmcnt(1)
	v_mfma_f32_16x16x32_bf16 v[18:21], v[34:37], v[18:21], 0
	ds_read_b128 v[34:37], v39 offset:64
	ds_read_b128 v[150:153], v51 offset:36928
	s_waitcnt lgkmcnt(0)
	v_mfma_f32_16x16x32_bf16 v[22:25], v[150:153], v[34:37], v[22:25]
	ds_read_b128 v[150:153], v51 offset:45888
	s_waitcnt lgkmcnt(0)
	v_mfma_f32_16x16x32_bf16 v[26:29], v[150:153], v[34:37], v[26:29]
	ds_read_b128 v[150:153], v51 offset:54848
	s_waitcnt lgkmcnt(0)
	v_mfma_f32_16x16x32_bf16 v[30:33], v[150:153], v[34:37], v[30:33]
	ds_read_b128 v[150:153], v51 offset:63808
	s_waitcnt lgkmcnt(0)
	v_mfma_f32_16x16x32_bf16 v[18:21], v[150:153], v[34:37], v[18:21]
	ds_read_b128 v[34:37], v39 offset:128
	ds_read_b128 v[150:153], v51 offset:36992
	s_waitcnt lgkmcnt(0)
	v_mfma_f32_16x16x32_bf16 v[22:25], v[150:153], v[34:37], v[22:25]
	ds_read_b128 v[150:153], v51 offset:45952
	s_waitcnt lgkmcnt(0)
	v_mfma_f32_16x16x32_bf16 v[26:29], v[150:153], v[34:37], v[26:29]
	ds_read_b128 v[150:153], v51 offset:54912
	s_waitcnt lgkmcnt(0)
	v_mfma_f32_16x16x32_bf16 v[30:33], v[150:153], v[34:37], v[30:33]
	ds_read_b128 v[150:153], v51 offset:63872
	s_waitcnt lgkmcnt(0)
	v_mfma_f32_16x16x32_bf16 v[18:21], v[150:153], v[34:37], v[18:21]
	ds_read_b128 v[34:37], v39 offset:192
	ds_read_b128 v[150:153], v51 offset:37056
	s_waitcnt lgkmcnt(0)
	v_mfma_f32_16x16x32_bf16 v[22:25], v[150:153], v[34:37], v[22:25]
	ds_read_b128 v[150:153], v51 offset:46016
	s_waitcnt lgkmcnt(0)
	v_mfma_f32_16x16x32_bf16 v[150:153], v[150:153], v[34:37], v[26:29]
	s_nop 2
	ds_read_b128 v[26:29], v51 offset:54976
	s_waitcnt lgkmcnt(0)
	v_mfma_f32_16x16x32_bf16 v[26:29], v[26:29], v[34:37], v[30:33]
	s_nop 2
	ds_read_b128 v[30:33], v51 offset:63936
	s_waitcnt lgkmcnt(0)
	v_mfma_f32_16x16x32_bf16 v[18:21], v[30:33], v[34:37], v[18:21]
	ds_read_b128 v[34:37], v39 offset:256
	ds_read_b128 v[30:33], v51 offset:37120
	s_waitcnt lgkmcnt(0)
	v_mfma_f32_16x16x32_bf16 v[22:25], v[30:33], v[34:37], v[22:25]
	ds_read_b128 v[30:33], v51 offset:46080
	s_waitcnt lgkmcnt(0)
	v_mfma_f32_16x16x32_bf16 v[30:33], v[30:33], v[34:37], v[150:153]
	s_nop 2
	ds_read_b128 v[150:153], v51 offset:55040
	s_waitcnt lgkmcnt(0)
	v_mfma_f32_16x16x32_bf16 v[26:29], v[150:153], v[34:37], v[26:29]
	ds_read_b128 v[150:153], v51 offset:64000
	v_ashrrev_i32_e32 v51, 31, v50
	s_waitcnt lgkmcnt(0)
	v_mfma_f32_16x16x32_bf16 v[18:21], v[150:153], v[34:37], v[18:21]
	v_cndmask_b32_e64 v34, 0, 1, s[76:77]
	v_cmp_ne_u32_e64 s[46:47], 1, v34
	s_cbranch_vccnz .LBB0_268
	v_sub_f32_e32 v37, v97, v41
	s_or_b32 s94, s78, s88
	v_mul_f32_e32 v37, 0x3fb8aa3b, v37
	v_or_b32_e32 v36, s94, v106
	v_readlane_b32 s94, v254, 32
	v_exp_f32_e32 v37, v37
	v_readlane_b32 s95, v254, 33
	s_nop 1
	v_mov_b64_e32 v[34:35], s[94:95]
	s_movk_i32 s94, 0x1c00
	v_mad_u64_u32 v[34:35], s[94:95], v36, s94, v[34:35]
	v_add_f32_e32 v36, v147, v148
	v_add_f32_e32 v36, v37, v36
	v_div_scale_f32 v37, s[94:95], v36, v36, 1.0
	v_rcp_f32_e32 v41, v37
	v_mad_i32_i24 v35, s79, v210, v35
	v_lshl_add_u64 v[34:35], s[2:3], 1, v[34:35]
	v_lshl_add_u64 v[34:35], v[50:51], 1, v[34:35]
	v_fma_f32 v96, -v37, v41, 1.0
	v_fmac_f32_e32 v41, v96, v41
	v_div_scale_f32 v96, vcc, 1.0, v36, 1.0
	v_mul_f32_e32 v147, v96, v41
	v_fma_f32 v148, -v37, v147, v96
	v_fmac_f32_e32 v147, v148, v41
	v_fma_f32 v37, -v37, v147, v96
	v_div_fmas_f32 v37, v37, v41, v147
	v_div_fixup_f32 v36, v37, v36, 1.0
	v_pk_mul_f32 v[24:25], v[24:25], v[36:37] op_sel_hi:[1,0]
	v_pk_mul_f32 v[22:23], v[22:23], v[36:37] op_sel_hi:[1,0]
	v_pk_mul_f32 v[32:33], v[32:33], v[36:37] op_sel_hi:[1,0]
	v_pk_mul_f32 v[30:31], v[30:31], v[36:37] op_sel_hi:[1,0]
	v_cvt_pk_bf16_f32 v22, v22, v23
	v_cvt_pk_bf16_f32 v23, v24, v25
	v_pk_mul_f32 v[20:21], v[36:37], v[20:21] op_sel_hi:[0,1]
	v_pk_mul_f32 v[18:19], v[36:37], v[18:19] op_sel_hi:[0,1]
	v_pk_mul_f32 v[28:29], v[36:37], v[28:29] op_sel_hi:[0,1]
	v_pk_mul_f32 v[26:27], v[36:37], v[26:27] op_sel_hi:[0,1]
	global_store_dwordx2 v[34:35], v[22:23], off offset:2048
	v_cvt_pk_bf16_f32 v22, v30, v31
	v_cvt_pk_bf16_f32 v23, v32, v33
	s_movk_i32 s95, 0x1c00
	s_movk_i32 s94, 0x80
	global_store_dwordx2 v[34:35], v[22:23], off offset:2080
	v_cvt_pk_bf16_f32 v22, v26, v27
	v_cvt_pk_bf16_f32 v23, v28, v29
	v_cvt_pk_bf16_f32 v18, v18, v19
	v_cvt_pk_bf16_f32 v19, v20, v21
	global_store_dwordx2 v[34:35], v[22:23], off offset:2112
	global_store_dwordx2 v[34:35], v[18:19], off offset:2144
